# ml_intra: 16 query-fragment loads issued before the item barrier; MFMA section without memory waits
# speedup vs baseline: 1.0029x; 1.0029x over previous
.LBB0_677:
	s_or_b64 exec, exec, s[56:57]
	s_and_saveexec_b64 s[64:65], s[8:9]
	s_cbranch_execz .Lmli_noq
	v_lshl_add_u64 v[198:199], s[54:55], 0, v[48:49]
	v_lshlrev_b64 v[198:199], 12, v[198:199]
	v_lshl_add_u64 v[198:199], s[46:47], 0, v[198:199]
	s_lshl_b32 s80, s63, 10
	v_lshl_add_u64 v[198:199], v[198:199], 0, s[80:81]
	v_mov_b32_e32 v202, v58
	v_mov_b32_e32 v203, v0
	v_lshl_add_u64 v[200:201], v[198:199], 0, v[202:203]
	global_load_dwordx4 v[126:129], v[200:201], off
	global_load_dwordx4 v[130:133], v[200:201], off offset:64
	global_load_dwordx4 v[134:137], v[200:201], off offset:128
	global_load_dwordx4 v[138:141], v[200:201], off offset:192
	global_load_dwordx4 v[142:145], v[200:201], off offset:256
	global_load_dwordx4 v[146:149], v[200:201], off offset:320
	global_load_dwordx4 v[150:153], v[200:201], off offset:384
	global_load_dwordx4 v[154:157], v[200:201], off offset:448
	global_load_dwordx4 v[158:161], v[200:201], off offset:512
	global_load_dwordx4 v[162:165], v[200:201], off offset:576
	global_load_dwordx4 v[166:169], v[200:201], off offset:640
	global_load_dwordx4 v[170:173], v[200:201], off offset:704
	global_load_dwordx4 v[174:177], v[200:201], off offset:768
	global_load_dwordx4 v[186:189], v[200:201], off offset:832
	global_load_dwordx4 v[190:193], v[200:201], off offset:896
	global_load_dwordx4 v[194:197], v[200:201], off offset:960
.Lmli_noq:
	s_or_b64 exec, exec, s[64:65]
	s_mov_b32 s44, s70
	s_waitcnt lgkmcnt(0)
	s_barrier
	s_add_i32 s44, s44, s33
	s_cmpk_gt_i32 s44, 0x7ff
	s_cselect_b32 s65, 0, 1
	s_cbranch_scc1 .LBB0_679
	s_ashr_i32 s56, s44, 9
	s_ashr_i32 s57, s56, 31
	s_lshl_b32 s45, s44, 4
	s_and_b32 s80, s45, 0x1fc0
	s_lshl_b64 s[56:57], s[56:57], 25
	v_lshl_add_u64 v[2:3], s[80:81], 0, v[44:45]
	s_add_u32 s56, s46, s56
	v_lshlrev_b64 v[2:3], 12, v[2:3]
	s_addc_u32 s57, s47, s57
	s_lshl_b32 s44, s44, 10
	v_lshl_add_u64 v[2:3], s[56:57], 0, v[2:3]
	s_and_b32 s80, s44, 0xc00
	v_lshl_add_u64 v[2:3], v[2:3], 0, s[80:81]
	v_mov_b32_e32 v57, v0
	v_lshl_add_u64 v[30:31], v[2:3], 0, v[56:57]
	global_load_dwordx4 v[2:5], v[30:31], off
	global_load_dwordx4 v[6:9], v[30:31], off offset:128
	global_load_dwordx4 v[10:13], v[30:31], off offset:256
	global_load_dwordx4 v[14:17], v[30:31], off offset:384
	global_load_dwordx4 v[18:21], v[30:31], off offset:512
	global_load_dwordx4 v[22:25], v[30:31], off offset:640
	global_load_dwordx4 v[26:29], v[30:31], off offset:768
	s_nop 0
	global_load_dwordx4 v[30:33], v[30:31], off offset:896
.LBB0_679:
	v_mov_b32_e32 v57, 0
	v_mov_b32_e32 v38, 0
	v_mov_b32_e32 v39, 0
	v_mov_b32_e32 v40, 0
	v_mov_b32_e32 v41, 0
	v_mov_b32_e32 v34, 0
	v_mov_b32_e32 v35, 0
	v_mov_b32_e32 v36, 0
	v_mov_b32_e32 v37, 0
	s_and_saveexec_b64 s[44:45], s[8:9]
	s_cbranch_execz .LBB0_681
	s_cmp_eq_u32 s65, 0
	s_cbranch_scc1 .Lmli_w0
	s_waitcnt vmcnt(8)
	s_branch .Lmli_go

.Lmli_go:
	ds_read_b128 v[100:103], v60
	ds_read_b128 v[104:107], v60 offset:16640
	ds_read_b128 v[108:111], v60 offset:64
	ds_read_b128 v[112:115], v60 offset:16704
	s_waitcnt lgkmcnt(2)
	v_mfma_f32_16x16x32_bf16 v[38:41], v[100:103], v[126:129], 0
	v_mfma_f32_16x16x32_bf16 v[34:37], v[104:107], v[126:129], 0
	ds_read_b128 v[100:103], v60 offset:128
	ds_read_b128 v[104:107], v60 offset:16768
	s_waitcnt lgkmcnt(2)
	v_mfma_f32_16x16x32_bf16 v[38:41], v[108:111], v[130:133], v[38:41]
	v_mfma_f32_16x16x32_bf16 v[34:37], v[112:115], v[130:133], v[34:37]
	ds_read_b128 v[108:111], v60 offset:192
	ds_read_b128 v[112:115], v60 offset:16832
	s_waitcnt lgkmcnt(2)
	v_mfma_f32_16x16x32_bf16 v[38:41], v[100:103], v[134:137], v[38:41]
	v_mfma_f32_16x16x32_bf16 v[34:37], v[104:107], v[134:137], v[34:37]
	ds_read_b128 v[100:103], v60 offset:256
	ds_read_b128 v[104:107], v60 offset:16896
	s_waitcnt lgkmcnt(2)
	v_mfma_f32_16x16x32_bf16 v[38:41], v[108:111], v[138:141], v[38:41]
	v_mfma_f32_16x16x32_bf16 v[34:37], v[112:115], v[138:141], v[34:37]
	ds_read_b128 v[108:111], v60 offset:320
	ds_read_b128 v[112:115], v60 offset:16960
	s_waitcnt lgkmcnt(2)
	v_mfma_f32_16x16x32_bf16 v[38:41], v[100:103], v[142:145], v[38:41]
	v_mfma_f32_16x16x32_bf16 v[34:37], v[104:107], v[142:145], v[34:37]
	ds_read_b128 v[100:103], v60 offset:384
	ds_read_b128 v[104:107], v60 offset:17024
	s_waitcnt lgkmcnt(2)
	v_mfma_f32_16x16x32_bf16 v[38:41], v[108:111], v[146:149], v[38:41]
	v_mfma_f32_16x16x32_bf16 v[34:37], v[112:115], v[146:149], v[34:37]
	ds_read_b128 v[108:111], v60 offset:448
	ds_read_b128 v[112:115], v60 offset:17088
	s_waitcnt lgkmcnt(2)
	v_mfma_f32_16x16x32_bf16 v[38:41], v[100:103], v[150:153], v[38:41]
	v_mfma_f32_16x16x32_bf16 v[34:37], v[104:107], v[150:153], v[34:37]
	ds_read_b128 v[100:103], v60 offset:512
	ds_read_b128 v[104:107], v60 offset:17152
	s_waitcnt lgkmcnt(2)
	v_mfma_f32_16x16x32_bf16 v[38:41], v[108:111], v[154:157], v[38:41]
	v_mfma_f32_16x16x32_bf16 v[34:37], v[112:115], v[154:157], v[34:37]
	ds_read_b128 v[108:111], v60 offset:576
	ds_read_b128 v[112:115], v60 offset:17216
	s_waitcnt lgkmcnt(2)
	v_mfma_f32_16x16x32_bf16 v[38:41], v[100:103], v[158:161], v[38:41]
	v_mfma_f32_16x16x32_bf16 v[34:37], v[104:107], v[158:161], v[34:37]
	ds_read_b128 v[100:103], v60 offset:640
	ds_read_b128 v[104:107], v60 offset:17280
	s_waitcnt lgkmcnt(2)
	v_mfma_f32_16x16x32_bf16 v[38:41], v[108:111], v[162:165], v[38:41]
	v_mfma_f32_16x16x32_bf16 v[34:37], v[112:115], v[162:165], v[34:37]
	ds_read_b128 v[108:111], v60 offset:704
	ds_read_b128 v[112:115], v60 offset:17344
	s_waitcnt lgkmcnt(2)
	v_mfma_f32_16x16x32_bf16 v[38:41], v[100:103], v[166:169], v[38:41]
	v_mfma_f32_16x16x32_bf16 v[34:37], v[104:107], v[166:169], v[34:37]
	ds_read_b128 v[100:103], v60 offset:768
	ds_read_b128 v[104:107], v60 offset:17408
	s_waitcnt lgkmcnt(2)
	v_mfma_f32_16x16x32_bf16 v[38:41], v[108:111], v[170:173], v[38:41]
	v_mfma_f32_16x16x32_bf16 v[34:37], v[112:115], v[170:173], v[34:37]
	ds_read_b128 v[108:111], v60 offset:832
	ds_read_b128 v[112:115], v60 offset:17472
	s_waitcnt lgkmcnt(2)
	v_mfma_f32_16x16x32_bf16 v[38:41], v[100:103], v[174:177], v[38:41]
	v_mfma_f32_16x16x32_bf16 v[34:37], v[104:107], v[174:177], v[34:37]
	ds_read_b128 v[100:103], v60 offset:896
	ds_read_b128 v[104:107], v60 offset:17536
	s_waitcnt lgkmcnt(2)
	v_mfma_f32_16x16x32_bf16 v[38:41], v[108:111], v[186:189], v[38:41]
	v_mfma_f32_16x16x32_bf16 v[34:37], v[112:115], v[186:189], v[34:37]
	ds_read_b128 v[108:111], v60 offset:960
	ds_read_b128 v[112:115], v60 offset:17600
	s_waitcnt lgkmcnt(2)
	v_mfma_f32_16x16x32_bf16 v[38:41], v[100:103], v[190:193], v[38:41]
	v_mfma_f32_16x16x32_bf16 v[34:37], v[104:107], v[190:193], v[34:37]
	s_waitcnt lgkmcnt(0)
	v_mfma_f32_16x16x32_bf16 v[38:41], v[108:111], v[194:197], v[38:41]
	v_mfma_f32_16x16x32_bf16 v[34:37], v[112:115], v[194:197], v[34:37]
